# EpiUp: no store-draining waits in sub-pass 7 and at tile top; pass A cumulative-decay scans of heads 1-3 interleaved
# speedup vs baseline: 1.0309x; 1.0097x over previous
; #define LAS __attribute__((address_space(3)))
; __device__ __forceinline__ void ssd_cs(const Args& a, LAS unsigned char* lds, const SeqInfo& si, int g, int lane, int mode, float* cdec) {
;     LAS float* cs = (LAS float*)(lds + L_CS); LAS float* dtl = cs + 256; LAS float* aux = cs + 512;
;     const float* dtv = (const float*)(a.ws + WS_DTV);
; #pragma unroll
;     for (int h4 = 0; h4 < 4; ++h4) {
;         const int h = g * 4 + h4;
;         float d = dtv[(size_t)(si.row0 + lane) * 8 + h]; d = lane >= si.pad ? d : 0.f;
;         const float av = -__expf(a.in[I_ALOG][h]);
;         float x = d * av;
; #pragma unroll
;         for (int o = 1; o < 64; o <<= 1) { const float y = __shfl_up(x, o); if (lane >= o) x += y; }
;         const float ce = __shfl(x, 63);
;         cs[h4 * 64 + lane] = x; dtl[h4 * 64 + lane] = d;
;         aux[h4 * 64 + lane] = mode == 0 ? __expf(ce - x) * d : __expf(x);
;         if (mode == 0 && lane == 0 && cdec) cdec[(size_t)si.slot * 8 + h] = __expf(ce);
;     }
.LBB0_249:
	s_or_b64 exec, exec, s[68:69]
	global_load_dword v12, v105, s[16:17] offset:4
	global_load_dword v16, v[0:1], off offset:4
	global_load_dword v13, v105, s[16:17] offset:8
	global_load_dword v17, v[0:1], off offset:8
	global_load_dword v14, v105, s[16:17] offset:12
	global_load_dword v18, v[0:1], off offset:12
	s_waitcnt vmcnt(0)
	v_mul_f32_e32 v12, 0x3fb8aa3b, v12
	v_mul_f32_e32 v13, 0x3fb8aa3b, v13
	v_mul_f32_e32 v14, 0x3fb8aa3b, v14
	v_exp_f32_e32 v12, v12
	v_exp_f32_e32 v13, v13
	v_exp_f32_e32 v14, v14
	v_cndmask_b32_e64 v16, v16, 0, vcc
	v_cndmask_b32_e64 v17, v17, 0, vcc
	v_cndmask_b32_e64 v18, v18, 0, vcc
	v_mul_f32_e64 v20, v16, -v12
	v_mul_f32_e64 v21, v17, -v13
	v_mul_f32_e64 v22, v18, -v14
	ds_bpermute_b32 v24, v2, v20
	ds_bpermute_b32 v25, v2, v21
	ds_bpermute_b32 v26, v2, v22
	s_waitcnt lgkmcnt(2)
	v_fma_f32 v24, v16, -v12, v24
	v_cndmask_b32_e64 v20, v24, v20, s[0:1]
	s_waitcnt lgkmcnt(1)
	v_fma_f32 v25, v17, -v13, v25
	v_cndmask_b32_e64 v21, v25, v21, s[0:1]
	s_waitcnt lgkmcnt(0)
	v_fma_f32 v26, v18, -v14, v26
	v_cndmask_b32_e64 v22, v26, v22, s[0:1]
	ds_bpermute_b32 v24, v3, v20
	ds_bpermute_b32 v25, v3, v21
	ds_bpermute_b32 v26, v3, v22
	s_waitcnt lgkmcnt(2)
	v_add_f32_e32 v24, v20, v24
	v_cndmask_b32_e64 v20, v24, v20, s[4:5]
	s_waitcnt lgkmcnt(1)
	v_add_f32_e32 v25, v21, v25
	v_cndmask_b32_e64 v21, v25, v21, s[4:5]
	s_waitcnt lgkmcnt(0)
	v_add_f32_e32 v26, v22, v26
	v_cndmask_b32_e64 v22, v26, v22, s[4:5]
	ds_bpermute_b32 v24, v4, v20
	ds_bpermute_b32 v25, v4, v21
	ds_bpermute_b32 v26, v4, v22
	s_waitcnt lgkmcnt(2)
	v_add_f32_e32 v24, v20, v24
	v_cndmask_b32_e64 v20, v24, v20, s[6:7]
	s_waitcnt lgkmcnt(1)
	v_add_f32_e32 v25, v21, v25
	v_cndmask_b32_e64 v21, v25, v21, s[6:7]
	s_waitcnt lgkmcnt(0)
	v_add_f32_e32 v26, v22, v26
	v_cndmask_b32_e64 v22, v26, v22, s[6:7]
	ds_bpermute_b32 v24, v5, v20
	ds_bpermute_b32 v25, v5, v21
	ds_bpermute_b32 v26, v5, v22
	s_waitcnt lgkmcnt(2)
	v_add_f32_e32 v24, v20, v24
	v_cndmask_b32_e64 v20, v24, v20, s[8:9]
	s_waitcnt lgkmcnt(1)
	v_add_f32_e32 v25, v21, v25
	v_cndmask_b32_e64 v21, v25, v21, s[8:9]
	s_waitcnt lgkmcnt(0)
	v_add_f32_e32 v26, v22, v26
	v_cndmask_b32_e64 v22, v26, v22, s[8:9]
	ds_bpermute_b32 v24, v6, v20
	ds_bpermute_b32 v25, v6, v21
	ds_bpermute_b32 v26, v6, v22
	s_waitcnt lgkmcnt(2)
	v_add_f32_e32 v24, v20, v24
	v_cndmask_b32_e64 v20, v24, v20, s[10:11]
	s_waitcnt lgkmcnt(1)
	v_add_f32_e32 v25, v21, v25
	v_cndmask_b32_e64 v21, v25, v21, s[10:11]
	s_waitcnt lgkmcnt(0)
	v_add_f32_e32 v26, v22, v26
	v_cndmask_b32_e64 v22, v26, v22, s[10:11]
	ds_bpermute_b32 v24, v7, v20
	ds_bpermute_b32 v25, v7, v21
	ds_bpermute_b32 v26, v7, v22
	s_waitcnt lgkmcnt(2)
	v_add_f32_e32 v24, v20, v24
	v_cndmask_b32_e64 v20, v24, v20, s[12:13]
	s_waitcnt lgkmcnt(1)
	v_add_f32_e32 v25, v21, v25
	v_cndmask_b32_e64 v21, v25, v21, s[12:13]
	s_waitcnt lgkmcnt(0)
	v_add_f32_e32 v26, v22, v26
	v_cndmask_b32_e64 v22, v26, v22, s[12:13]
	ds_bpermute_b32 v28, v162, v20
	ds_bpermute_b32 v29, v162, v21
	ds_bpermute_b32 v30, v162, v22
	ds_write_b32 v134, v20
	ds_write_b32 v135, v16
	ds_write_b32 v137, v21
	ds_write_b32 v138, v17
	ds_write_b32 v140, v22
	ds_write_b32 v141, v18
	s_waitcnt lgkmcnt(6)
	v_sub_f32_e32 v24, v28, v20
	v_sub_f32_e32 v25, v29, v21
	v_sub_f32_e32 v26, v30, v22
	v_mul_f32_e32 v24, 0x3fb8aa3b, v24
	v_mul_f32_e32 v25, 0x3fb8aa3b, v25
	v_mul_f32_e32 v26, 0x3fb8aa3b, v26
	v_exp_f32_e32 v24, v24
	v_exp_f32_e32 v25, v25
	v_exp_f32_e32 v26, v26
	v_mul_f32_e32 v24, v16, v24
	v_mul_f32_e32 v25, v17, v25
	v_mul_f32_e32 v26, v18, v26
	ds_write_b32 v136, v24
	ds_write_b32 v139, v25
	ds_write_b32 v142, v26
	s_and_saveexec_b64 s[16:17], s[2:3]
	s_cbranch_execz .LBB0_255
	v_mul_f32_e32 v28, 0x3fb8aa3b, v28
	v_mul_f32_e32 v29, 0x3fb8aa3b, v29
	v_mul_f32_e32 v30, 0x3fb8aa3b, v30
	v_exp_f32_e32 v28, v28
	v_exp_f32_e32 v29, v29
	v_exp_f32_e32 v30, v30
	s_lshl_b32 s55, s34, 2
	v_mov_b32_e32 v24, s55
	global_store_dword v24, v28, s[20:21] offset:4
	global_store_dword v24, v29, s[20:21] offset:8
	global_store_dword v24, v30, s[20:21] offset:12

; template <class Epi>
; __device__ __forceinline__ void gemm_phase(LAS unsigned char* lds, const Gemm g, const StaticOrder& S, const Epi& E) {
;     ...
;         E(acc, cur, wr, wc, fr, fq);
;         if (!has_next) break;
; #pragma unroll
;         for (int a = 0; a < 2; ++a)
; #pragma unroll
;             for (int b = 0; b < 2; ++b)
; #pragma unroll
;                 for (int m = 0; m < 4; ++m)
; #pragma unroll
;                     for (int n = 0; n < 2; ++n) acc[a][b][m][n] = (f32x4){0.f, 0.f, 0.f, 0.f};
;         cur = nxt; cA = nA; cB = nB; ++ui;
.LBB0_1131:
	s_ashr_i32 s31, s30, 31
	s_lshl_b64 s[36:37], s[30:31], 19
	s_add_u32 s36, s18, s36
	s_addc_u32 s37, s19, s37
	s_and_b64 s[2:3], s[2:3], exec
	s_cselect_b32 s5, s37, s41
	s_cselect_b32 s31, s36, s40
	s_add_u32 s45, s40, 0x100
	v_mov_b32_e32 v0, 0
	s_addc_u32 s46, s41, 0
	s_mov_b32 s47, -2
	v_mov_b32_e32 v1, v0
	v_mov_b32_e32 v2, v0
	v_mov_b32_e32 v3, v0
	v_mov_b32_e32 v32, v0
	v_mov_b32_e32 v33, v0
	v_mov_b32_e32 v34, v0
	v_mov_b32_e32 v35, v0
	v_mov_b32_e32 v4, v0
	v_mov_b32_e32 v5, v0
	v_mov_b32_e32 v6, v0
	v_mov_b32_e32 v7, v0
	v_mov_b32_e32 v36, v0
	v_mov_b32_e32 v37, v0
	v_mov_b32_e32 v38, v0
	v_mov_b32_e32 v39, v0
	v_mov_b32_e32 v8, v0
	v_mov_b32_e32 v9, v0
	v_mov_b32_e32 v10, v0
	v_mov_b32_e32 v11, v0
	v_mov_b32_e32 v40, v0
	v_mov_b32_e32 v41, v0
	v_mov_b32_e32 v42, v0
	v_mov_b32_e32 v43, v0
	v_mov_b32_e32 v12, v0
	v_mov_b32_e32 v13, v0
	v_mov_b32_e32 v14, v0
	v_mov_b32_e32 v15, v0
	v_mov_b32_e32 v44, v0
	v_mov_b32_e32 v45, v0
	v_mov_b32_e32 v46, v0
	v_mov_b32_e32 v47, v0
	v_mov_b32_e32 v16, v0
	v_mov_b32_e32 v17, v0
	v_mov_b32_e32 v18, v0
	v_mov_b32_e32 v19, v0
	v_mov_b32_e32 v48, v0
	v_mov_b32_e32 v49, v0
	v_mov_b32_e32 v50, v0
	v_mov_b32_e32 v51, v0
	v_mov_b32_e32 v20, v0
	v_mov_b32_e32 v21, v0
	v_mov_b32_e32 v22, v0
	v_mov_b32_e32 v23, v0
	v_mov_b32_e32 v52, v0
	v_mov_b32_e32 v53, v0
	v_mov_b32_e32 v54, v0
	v_mov_b32_e32 v55, v0
	v_mov_b32_e32 v24, v0
	v_mov_b32_e32 v25, v0
	v_mov_b32_e32 v26, v0
	v_mov_b32_e32 v27, v0
	v_mov_b32_e32 v56, v0
	v_mov_b32_e32 v57, v0
	v_mov_b32_e32 v58, v0
	v_mov_b32_e32 v59, v0
	v_mov_b32_e32 v28, v0
	v_mov_b32_e32 v29, v0
	v_mov_b32_e32 v30, v0
	v_mov_b32_e32 v31, v0
	v_mov_b32_e32 v60, v0
	v_mov_b32_e32 v61, v0
	v_mov_b32_e32 v62, v0
	v_mov_b32_e32 v63, v0
	v_mov_b32_e32 v64, v0
	v_mov_b32_e32 v65, v0
	v_mov_b32_e32 v66, v0
	v_mov_b32_e32 v67, v0
	v_mov_b32_e32 v112, v0
	v_mov_b32_e32 v113, v0
	v_mov_b32_e32 v114, v0
	v_mov_b32_e32 v115, v0
	v_mov_b32_e32 v68, v0
	v_mov_b32_e32 v69, v0
	v_mov_b32_e32 v70, v0
	v_mov_b32_e32 v71, v0
	v_mov_b32_e32 v116, v0
	v_mov_b32_e32 v117, v0
	v_mov_b32_e32 v118, v0
	v_mov_b32_e32 v119, v0
	v_mov_b32_e32 v72, v0
	v_mov_b32_e32 v73, v0
	v_mov_b32_e32 v74, v0
	v_mov_b32_e32 v75, v0
	v_mov_b32_e32 v120, v0
	v_mov_b32_e32 v121, v0
	v_mov_b32_e32 v122, v0
	v_mov_b32_e32 v123, v0
	v_mov_b32_e32 v76, v0
	v_mov_b32_e32 v77, v0
	v_mov_b32_e32 v78, v0
	v_mov_b32_e32 v79, v0
	v_mov_b32_e32 v124, v0
	v_mov_b32_e32 v125, v0
	v_mov_b32_e32 v126, v0
	v_mov_b32_e32 v127, v0
	v_mov_b32_e32 v80, v0
	v_mov_b32_e32 v81, v0
	v_mov_b32_e32 v82, v0
	v_mov_b32_e32 v83, v0
	v_mov_b32_e32 v128, v0
	v_mov_b32_e32 v129, v0
	v_mov_b32_e32 v130, v0
	v_mov_b32_e32 v131, v0
	v_mov_b32_e32 v84, v0
	v_mov_b32_e32 v85, v0
	v_mov_b32_e32 v86, v0
	v_mov_b32_e32 v87, v0
	v_mov_b32_e32 v132, v0
	v_mov_b32_e32 v133, v0
	v_mov_b32_e32 v134, v0
	v_mov_b32_e32 v135, v0
	v_mov_b32_e32 v88, v0
	v_mov_b32_e32 v89, v0
	v_mov_b32_e32 v90, v0
	v_mov_b32_e32 v91, v0
	v_mov_b32_e32 v136, v0
	v_mov_b32_e32 v137, v0
	v_mov_b32_e32 v138, v0
	v_mov_b32_e32 v139, v0
	v_mov_b32_e32 v92, v0
	v_mov_b32_e32 v93, v0
	v_mov_b32_e32 v94, v0
	v_mov_b32_e32 v95, v0
	v_mov_b32_e32 v140, v0
	v_mov_b32_e32 v141, v0
	v_mov_b32_e32 v142, v0
	v_mov_b32_e32 v143, v0

; #define LAS __attribute__((address_space(3)))
; __device__ __forceinline__ float bf2f(unsigned v) { return __uint_as_float(v << 16); }
;     __device__ __forceinline__ void operator()(const f32x4 (&acc)[2][2][4][2], const pg8::Unit& u, int wr, int wc, int fr_, int fq_) const {
;     ...
;         for (int sp = 0; sp < 8; ++sp) {
;             const int ai = sp >> 2, n = (sp >> 1) & 1, bj = sp & 1;
;             const int rowbase = 248 * u.pm + 62 * (2 * ai + wr) - 2;
;             const f32x4 w0 = wn[0], w1 = wn[1], w2 = wn[2], bb = wn[3];
;             if (sp < 7) { const int sq = sp + 1, n2 = (sq >> 1) & 1, bj2 = sq & 1, colb = bj2 * DFF + j0 + 4 * n2;
;                 wn[0] = *(const f32x4*)(cw + colb); wn[1] = *(const f32x4*)(cw + NUP + colb); wn[2] = *(const f32x4*)(cw + 2 * NUP + colb); wn[3] = *(const f32x4*)(cb + colb); }
; #pragma unroll
;             for (int m = 0; m < 4; ++m) { const f32x4 v = acc[ai][bj][m][n] * sc[ai][m];
;                 u32x2 w; w.x = pk2(v[0], v[1]); w.y = pk2(v[2], v[3]); *(LAS u32x2*)(slab + (16 * m + fr) * SLAB_LD + fq * 8) = w; }
;             f32x4 p2, p1;
;             { const int h1 = rs > 0 ? 4 * rs - 1 : 0, h2 = rs > 0 ? 4 * rs - 2 : 0;
;                 const u32x2 q1 = *(const LAS u32x2*)(slab + h1 * SLAB_LD + cq * 8), q2 = *(const LAS u32x2*)(slab + h2 * SLAB_LD + cq * 8);
;                 p1[0] = bf2f(q1.x & 0xffff); p1[1] = bf2f(q1.x >> 16); p1[2] = bf2f(q1.y & 0xffff); p1[3] = bf2f(q1.y >> 16);
;                 p2[0] = bf2f(q2.x & 0xffff); p2[1] = bf2f(q2.x >> 16); p2[2] = bf2f(q2.y & 0xffff); p2[3] = bf2f(q2.y >> 16); }
; #pragma unroll
;             for (int i = 0; i < 4; ++i) {
;                 const int lr = 4 * rs + i, row = rowbase + lr;
;                 const u32x2 q0 = *(const LAS u32x2*)(slab + lr * SLAB_LD + cq * 8);
;                 f32x4 cur; cur[0] = bf2f(q0.x & 0xffff); cur[1] = bf2f(q0.x >> 16); cur[2] = bf2f(q0.y & 0xffff); cur[3] = bf2f(q0.y >> 16);
;                 const bool smp = row >= RP;
;                 const int t = smp ? ((row - RP) & (DSEQ - 1)) : (row & (SEQ - 1));
;                 const bool valid = (lr >= 2) && (row < R) && (t >= 2);
;                 const f32x4 cv = bb + w0 * p2 + w1 * p1 + w2 * cur;
;                 p2 = p1; p1 = cur;
;                 if (bj == 0) { cgv[i][0] = cv[0]; cgv[i][1] = cv[1]; cgv[i][2] = cv[2]; cgv[i][3] = cv[3]; }
.LBB0_1141:
	s_or_b64 exec, exec, s[46:47]
	v_add_co_u32_e32 v112, vcc, 0x2000, v196
	v_mov_b32_e32 v211, v210
	s_nop 0
	v_addc_co_u32_e32 v113, vcc, 0, v197, vcc
	v_add_co_u32_e32 v114, vcc, 0x2000, v198
	v_mov_b32_e32 v144, v210
	v_addc_co_u32_e32 v115, vcc, 0, v199, vcc
	global_load_dwordx4 v[132:135], v[112:113], off offset:3088
	global_load_dwordx4 v[136:139], v[114:115], off offset:3088
	v_add_co_u32_e32 v112, vcc, 0x2000, v200
	v_mov_b32_e32 v145, v210
	s_nop 0
	v_addc_co_u32_e32 v113, vcc, 0, v201, vcc
	global_load_dwordx4 v[128:131], v[112:113], off offset:3088
	v_add_co_u32_e32 v112, vcc, 0x2000, v202
	v_pk_mul_f32 v[94:95], v[94:95], v[144:145]
	s_nop 0
	v_addc_co_u32_e32 v113, vcc, 0, v203, vcc
	global_load_dwordx4 v[140:143], v[112:113], off offset:3088
	global_load_dwordx4 v[120:123], v[196:197], off
	global_load_dwordx4 v[116:119], v[198:199], off
	s_nop 0
	global_load_dwordx4 v[112:115], v[200:201], off
	global_load_dwordx4 v[124:127], v[202:203], off
	v_pk_mul_f32 v[92:93], v[92:93], v[210:211]
	v_mov_b32_e32 v209, v208
	v_cvt_pk_bf16_f32 v92, v92, v93
	v_cvt_pk_bf16_f32 v93, v94, v95
	v_mov_b32_e32 v207, v206
	v_mov_b32_e32 v205, v204
	ds_write_b64 v227, v[92:93]
	v_mov_b32_e32 v92, v208
	v_mov_b32_e32 v93, v208
	v_mov_b32_e32 v146, v206
	v_mov_b32_e32 v147, v206
	v_mov_b32_e32 v148, v204
	v_mov_b32_e32 v149, v204
	v_pk_mul_f32 v[90:91], v[90:91], v[92:93]
	v_pk_mul_f32 v[88:89], v[88:89], v[208:209]
	v_pk_mul_f32 v[86:87], v[86:87], v[146:147]
	v_pk_mul_f32 v[84:85], v[84:85], v[206:207]
	v_pk_mul_f32 v[82:83], v[82:83], v[148:149]
	v_pk_mul_f32 v[80:81], v[80:81], v[204:205]
	v_cvt_pk_bf16_f32 v88, v88, v89
	v_cvt_pk_bf16_f32 v89, v90, v91
	v_cvt_pk_bf16_f32 v84, v84, v85
	v_cvt_pk_bf16_f32 v85, v86, v87
	v_cvt_pk_bf16_f32 v80, v80, v81
	v_cvt_pk_bf16_f32 v81, v82, v83
	ds_write_b64 v227, v[88:89] offset:640
	ds_write_b64 v227, v[84:85] offset:1280
	ds_write_b64 v227, v[80:81] offset:1920
	ds_read_b64 v[80:81], v226
	ds_read_b64 v[150:151], v225
	ds_read_b64 v[84:85], v224
	ds_read_b64 v[94:95], v228
	v_pk_mul_f32 v[78:79], v[78:79], v[144:145]
	v_pk_mul_f32 v[76:77], v[76:77], v[210:211]
	v_pk_mul_f32 v[74:75], v[74:75], v[92:93]
	v_pk_mul_f32 v[72:73], v[72:73], v[208:209]
	v_pk_mul_f32 v[70:71], v[70:71], v[146:147]
	v_pk_mul_f32 v[68:69], v[68:69], v[206:207]
	v_pk_mul_f32 v[66:67], v[66:67], v[148:149]
	v_pk_mul_f32 v[64:65], v[64:65], v[204:205]
	v_cvt_pk_bf16_f32 v76, v76, v77
	v_cvt_pk_bf16_f32 v77, v78, v79
	v_cvt_pk_bf16_f32 v72, v72, v73
	v_cvt_pk_bf16_f32 v73, v74, v75
	v_cvt_pk_bf16_f32 v68, v68, v69
	v_cvt_pk_bf16_f32 v69, v70, v71
	v_cvt_pk_bf16_f32 v64, v64, v65
	v_cvt_pk_bf16_f32 v65, v66, v67
	s_waitcnt lgkmcnt(3)
	v_lshlrev_b32_e32 v88, 16, v80
	v_and_b32_e32 v89, 0xffff0000, v80
	v_lshlrev_b32_e32 v90, 16, v81
	v_and_b32_e32 v91, 0xffff0000, v81
	ds_read2_b64 v[80:83], v225 offset0:5 offset1:10
	ds_write_b64 v227, v[76:77]
	ds_write_b64 v227, v[72:73] offset:640
	ds_write_b64 v227, v[68:69] offset:1280
	ds_write_b64 v227, v[64:65] offset:1920
	ds_read_b64 v[64:65], v226
	ds_read_b64 v[66:67], v225
	s_waitcnt lgkmcnt(9)
	v_lshlrev_b32_e32 v86, 16, v150
	v_and_b32_e32 v87, 0xffff0000, v150
	v_lshlrev_b32_e32 v68, 16, v151
	v_and_b32_e32 v69, 0xffff0000, v151
	s_waitcnt lgkmcnt(1)
	v_lshlrev_b32_e32 v78, 16, v64
	v_and_b32_e32 v79, 0xffff0000, v64
	v_lshlrev_b32_e32 v92, 16, v65
	v_and_b32_e32 v93, 0xffff0000, v65
	s_waitcnt lgkmcnt(0)
	v_lshlrev_b32_e32 v64, 16, v66
	v_and_b32_e32 v65, 0xffff0000, v66
	v_lshlrev_b32_e32 v66, 16, v67
	v_and_b32_e32 v67, 0xffff0000, v67
	s_and_saveexec_b64 s[46:47], s[38:39]
	s_cbranch_execz .LBB0_1143
	v_lshlrev_b32_e32 v74, 16, v94
	v_and_b32_e32 v75, 0xffff0000, v94
	v_lshlrev_b32_e32 v76, 16, v95
	v_and_b32_e32 v77, 0xffff0000, v95
	v_pk_fma_f32 v[74:75], v[104:105], v[74:75], v[108:109]
	v_pk_fma_f32 v[76:77], v[106:107], v[76:77], v[110:111]
	v_pk_fma_f32 v[74:75], v[100:101], v[88:89], v[74:75]
	v_pk_fma_f32 v[76:77], v[102:103], v[90:91], v[76:77]
	v_pk_fma_f32 v[74:75], v[96:97], v[86:87], v[74:75]
	v_pk_fma_f32 v[76:77], v[98:99], v[68:69], v[76:77]
	v_mul_f32_e32 v144, v74, v74
	v_mul_f32_e32 v94, v76, v76
	v_mul_f32_e32 v95, v77, v77
	v_mul_f32_e32 v145, v75, v75
	v_fmamk_f32 v94, v94, 0xbdd2d3e2, v221
	v_fmamk_f32 v95, v95, 0xbdd2d3e2, v221
	v_fmamk_f32 v144, v144, 0xbdd2d3e2, v221
	v_fmamk_f32 v145, v145, 0xbdd2d3e2, v221
	v_mul_f32_e32 v94, v76, v94
	v_mul_f32_e32 v95, v77, v95
	v_mul_f32_e32 v144, v74, v144
	v_mul_f32_e32 v145, v75, v145
	v_exp_f32_e32 v94, v94
	v_exp_f32_e32 v95, v95
	v_exp_f32_e32 v144, v144
	v_exp_f32_e32 v145, v145
	ds_read_b64 v[70:71], v228
	v_add_f32_e32 v94, 1.0, v94
	v_add_f32_e32 v95, 1.0, v95
	v_add_f32_e32 v144, 1.0, v144
	v_add_f32_e32 v145, 1.0, v145
	v_rcp_f32_e32 v94, v94
	v_rcp_f32_e32 v95, v95
	v_rcp_f32_e32 v144, v144
	v_rcp_f32_e32 v145, v145
	s_waitcnt lgkmcnt(0)
	v_lshlrev_b32_e32 v72, 16, v70
	v_and_b32_e32 v73, 0xffff0000, v70
	v_lshlrev_b32_e32 v70, 16, v71
	v_and_b32_e32 v71, 0xffff0000, v71
	s_waitcnt vmcnt(4)
	v_pk_fma_f32 v[72:73], v[132:133], v[72:73], v[140:141]
	v_pk_fma_f32 v[70:71], v[134:135], v[70:71], v[142:143]
	v_pk_fma_f32 v[72:73], v[136:137], v[78:79], v[72:73]
	v_pk_fma_f32 v[70:71], v[138:139], v[92:93], v[70:71]
	v_pk_fma_f32 v[72:73], v[128:129], v[64:65], v[72:73]
	v_pk_fma_f32 v[70:71], v[130:131], v[66:67], v[70:71]
	v_pk_mul_f32 v[76:77], v[76:77], v[94:95]
	v_pk_mul_f32 v[74:75], v[74:75], v[144:145]
	v_pk_mul_f32 v[70:71], v[76:77], v[70:71]
	v_pk_mul_f32 v[72:73], v[74:75], v[72:73]
	v_cvt_pk_bf16_f32 v71, v70, v71
	v_cvt_pk_bf16_f32 v70, v72, v73
	v_mov_b64_e32 v[72:73], s[8:9]
	v_mad_i64_i32 v[72:73], s[38:39], v241, s83, v[72:73]
	v_lshl_add_u64 v[72:73], v[194:195], 1, v[72:73]
	global_store_dwordx2 v[72:73], v[70:71], off offset:8

; #define LAS __attribute__((address_space(3)))
; __device__ __forceinline__ float bf2f(unsigned v) { return __uint_as_float(v << 16); }
;     __device__ __forceinline__ void operator()(const f32x4 (&acc)[2][2][4][2], const pg8::Unit& u, int wr, int wc, int fr_, int fq_) const {
;     ...
;             if (sp < 7) { const int sq = sp + 1, n2 = (sq >> 1) & 1, bj2 = sq & 1, colb = bj2 * DFF + j0 + 4 * n2;
;                 wn[0] = *(const f32x4*)(cw + colb); wn[1] = *(const f32x4*)(cw + NUP + colb); wn[2] = *(const f32x4*)(cw + 2 * NUP + colb); wn[3] = *(const f32x4*)(cb + colb); }
; #pragma unroll
;             for (int m = 0; m < 4; ++m) { const f32x4 v = acc[ai][bj][m][n] * sc[ai][m];
;                 u32x2 w; w.x = pk2(v[0], v[1]); w.y = pk2(v[2], v[3]); *(LAS u32x2*)(slab + (16 * m + fr) * SLAB_LD + fq * 8) = w; }
;             f32x4 p2, p1;
;             { const int h1 = rs > 0 ? 4 * rs - 1 : 0, h2 = rs > 0 ? 4 * rs - 2 : 0;
;                 const u32x2 q1 = *(const LAS u32x2*)(slab + h1 * SLAB_LD + cq * 8), q2 = *(const LAS u32x2*)(slab + h2 * SLAB_LD + cq * 8);
;                 p1[0] = bf2f(q1.x & 0xffff); p1[1] = bf2f(q1.x >> 16); p1[2] = bf2f(q1.y & 0xffff); p1[3] = bf2f(q1.y >> 16);
;                 p2[0] = bf2f(q2.x & 0xffff); p2[1] = bf2f(q2.x >> 16); p2[2] = bf2f(q2.y & 0xffff); p2[3] = bf2f(q2.y >> 16); }
; #pragma unroll
;             for (int i = 0; i < 4; ++i) {
;                 const int lr = 4 * rs + i, row = rowbase + lr;
;                 const u32x2 q0 = *(const LAS u32x2*)(slab + lr * SLAB_LD + cq * 8);
;                 f32x4 cur; cur[0] = bf2f(q0.x & 0xffff); cur[1] = bf2f(q0.x >> 16); cur[2] = bf2f(q0.y & 0xffff); cur[3] = bf2f(q0.y >> 16);
;                 const bool smp = row >= RP;
;                 const int t = smp ? ((row - RP) & (DSEQ - 1)) : (row & (SEQ - 1));
;                 const bool valid = (lr >= 2) && (row < R) && (t >= 2);
;                 const f32x4 cv = bb + w0 * p2 + w1 * p1 + w2 * cur;
;                 p2 = p1; p1 = cur;
;                 if (bj == 0) { cgv[i][0] = cv[0]; cgv[i][1] = cv[1]; cgv[i][2] = cv[2]; cgv[i][3] = cv[3]; }
;                 else { u32x2 w; w.x = pk2(gelu_tanh(cgv[i][0]) * cv[0], gelu_tanh(cgv[i][1]) * cv[1]); w.y = pk2(gelu_tanh(cgv[i][2]) * cv[2], gelu_tanh(cgv[i][3]) * cv[3]); if (valid) *(u32x2*)(act + (size_t)row * DFF + j0 + 4 * n) = w; }
.LBB0_1157:
	s_or_b64 exec, exec, s[42:43]
	v_lshl_add_u64 v[32:33], v[196:197], 0, s[24:25]
	v_lshl_add_u64 v[34:35], v[198:199], 0, s[24:25]
	v_lshl_add_u64 v[44:45], v[200:201], 0, s[24:25]
	v_lshl_add_u64 v[46:47], v[202:203], 0, s[24:25]
	global_load_dwordx4 v[40:43], v[32:33], off
	global_load_dwordx4 v[36:39], v[34:35], off
	s_nop 0
	global_load_dwordx4 v[32:35], v[44:45], off
	s_nop 0
	global_load_dwordx4 v[44:47], v[46:47], off
	v_mov_b32_e32 v97, v96
	v_mov_b32_e32 v48, v96
	v_mov_b32_e32 v49, v96
	v_pk_mul_f32 v[30:31], v[30:31], v[48:49]
	v_pk_mul_f32 v[28:29], v[28:29], v[96:97]
	v_mov_b32_e32 v103, v102
	v_cvt_pk_bf16_f32 v28, v28, v29
	v_cvt_pk_bf16_f32 v29, v30, v31
	v_mov_b32_e32 v101, v100
	v_mov_b32_e32 v99, v98
	ds_write_b64 v227, v[28:29]
	v_mov_b32_e32 v28, v102
	v_mov_b32_e32 v29, v102
	v_mov_b32_e32 v50, v100
	v_mov_b32_e32 v51, v100
	v_mov_b32_e32 v52, v98
	v_mov_b32_e32 v53, v98
	v_pk_mul_f32 v[26:27], v[26:27], v[28:29]
	v_pk_mul_f32 v[24:25], v[24:25], v[102:103]
	v_pk_mul_f32 v[22:23], v[22:23], v[50:51]
	v_pk_mul_f32 v[20:21], v[20:21], v[100:101]
	v_pk_mul_f32 v[18:19], v[18:19], v[52:53]
	v_pk_mul_f32 v[16:17], v[16:17], v[98:99]
	v_cvt_pk_bf16_f32 v24, v24, v25
	v_cvt_pk_bf16_f32 v25, v26, v27
	v_cvt_pk_bf16_f32 v20, v20, v21
	v_cvt_pk_bf16_f32 v21, v22, v23
	v_cvt_pk_bf16_f32 v16, v16, v17
	v_cvt_pk_bf16_f32 v17, v18, v19
	ds_write_b64 v227, v[24:25] offset:640
	ds_write_b64 v227, v[20:21] offset:1280
	ds_write_b64 v227, v[16:17] offset:1920
	ds_read_b64 v[16:17], v226
	ds_read_b64 v[56:57], v225
	ds_read_b64 v[20:21], v224
	ds_read_b64 v[30:31], v228
	v_pk_mul_f32 v[14:15], v[14:15], v[48:49]
	v_pk_mul_f32 v[12:13], v[12:13], v[96:97]
	v_pk_mul_f32 v[10:11], v[10:11], v[28:29]
	v_pk_mul_f32 v[8:9], v[8:9], v[102:103]
	v_pk_mul_f32 v[6:7], v[6:7], v[50:51]
	v_pk_mul_f32 v[4:5], v[4:5], v[100:101]
	v_pk_mul_f32 v[2:3], v[2:3], v[52:53]
	v_pk_mul_f32 v[0:1], v[0:1], v[98:99]
	v_cvt_pk_bf16_f32 v12, v12, v13
	v_cvt_pk_bf16_f32 v13, v14, v15
	v_cvt_pk_bf16_f32 v8, v8, v9
	v_cvt_pk_bf16_f32 v9, v10, v11
	v_cvt_pk_bf16_f32 v4, v4, v5
	v_cvt_pk_bf16_f32 v5, v6, v7
	v_cvt_pk_bf16_f32 v0, v0, v1
	v_cvt_pk_bf16_f32 v1, v2, v3
	s_waitcnt lgkmcnt(3)
	v_lshlrev_b32_e32 v24, 16, v16
	v_and_b32_e32 v25, 0xffff0000, v16
	v_lshlrev_b32_e32 v26, 16, v17
	v_and_b32_e32 v27, 0xffff0000, v17
	ds_read2_b64 v[16:19], v225 offset0:5 offset1:10
	ds_write_b64 v227, v[12:13]
	ds_write_b64 v227, v[8:9] offset:640
	ds_write_b64 v227, v[4:5] offset:1280
	ds_write_b64 v227, v[0:1] offset:1920
	ds_read_b64 v[0:1], v226
	ds_read_b64 v[2:3], v225
	s_waitcnt lgkmcnt(9)
	v_lshlrev_b32_e32 v22, 16, v56
	v_and_b32_e32 v23, 0xffff0000, v56
	v_lshlrev_b32_e32 v4, 16, v57
	v_and_b32_e32 v5, 0xffff0000, v57
	s_waitcnt lgkmcnt(1)
	v_lshlrev_b32_e32 v14, 16, v0
	v_and_b32_e32 v15, 0xffff0000, v0
	v_lshlrev_b32_e32 v28, 16, v1
	v_and_b32_e32 v29, 0xffff0000, v1
	s_waitcnt lgkmcnt(0)
	v_lshlrev_b32_e32 v0, 16, v2
	v_and_b32_e32 v1, 0xffff0000, v2
	v_lshlrev_b32_e32 v2, 16, v3
	v_and_b32_e32 v3, 0xffff0000, v3
	s_waitcnt vmcnt(0)
	s_and_saveexec_b64 s[42:43], s[38:39]
	s_cbranch_execz .LBB0_1159
	v_lshlrev_b32_e32 v10, 16, v30
	v_and_b32_e32 v11, 0xffff0000, v30
	v_lshlrev_b32_e32 v12, 16, v31
	v_and_b32_e32 v13, 0xffff0000, v31
	v_pk_fma_f32 v[10:11], v[72:73], v[10:11], v[76:77]
	v_pk_fma_f32 v[12:13], v[74:75], v[12:13], v[78:79]
	v_pk_fma_f32 v[10:11], v[68:69], v[24:25], v[10:11]
	v_pk_fma_f32 v[12:13], v[70:71], v[26:27], v[12:13]
	v_pk_fma_f32 v[10:11], v[64:65], v[22:23], v[10:11]
	v_pk_fma_f32 v[12:13], v[66:67], v[4:5], v[12:13]
	v_mul_f32_e32 v48, v10, v10
	v_mul_f32_e32 v30, v12, v12
	v_mul_f32_e32 v31, v13, v13
	v_mul_f32_e32 v49, v11, v11
	v_fmamk_f32 v30, v30, 0xbdd2d3e2, v221
	v_fmamk_f32 v31, v31, 0xbdd2d3e2, v221
	v_fmamk_f32 v48, v48, 0xbdd2d3e2, v221
	v_fmamk_f32 v49, v49, 0xbdd2d3e2, v221
	v_mul_f32_e32 v30, v12, v30
	v_mul_f32_e32 v31, v13, v31
	v_mul_f32_e32 v48, v10, v48
	v_mul_f32_e32 v49, v11, v49
	v_exp_f32_e32 v30, v30
	v_exp_f32_e32 v31, v31
	v_exp_f32_e32 v48, v48
	v_exp_f32_e32 v49, v49
	ds_read_b64 v[6:7], v228
	v_add_f32_e32 v30, 1.0, v30
	v_add_f32_e32 v31, 1.0, v31
	v_add_f32_e32 v48, 1.0, v48
	v_add_f32_e32 v49, 1.0, v49
	v_rcp_f32_e32 v30, v30
	v_rcp_f32_e32 v31, v31
	v_rcp_f32_e32 v48, v48
	v_rcp_f32_e32 v49, v49
	s_waitcnt lgkmcnt(0)
	v_lshlrev_b32_e32 v8, 16, v6
	v_and_b32_e32 v9, 0xffff0000, v6
	v_lshlrev_b32_e32 v6, 16, v7
	v_and_b32_e32 v7, 0xffff0000, v7
	v_pk_fma_f32 v[8:9], v[40:41], v[8:9], v[44:45]
	v_pk_fma_f32 v[6:7], v[42:43], v[6:7], v[46:47]
	v_pk_fma_f32 v[8:9], v[36:37], v[14:15], v[8:9]
	v_pk_fma_f32 v[6:7], v[38:39], v[28:29], v[6:7]
	v_pk_fma_f32 v[8:9], v[32:33], v[0:1], v[8:9]
	v_pk_fma_f32 v[6:7], v[34:35], v[2:3], v[6:7]
	v_pk_mul_f32 v[12:13], v[12:13], v[30:31]
	v_pk_mul_f32 v[10:11], v[10:11], v[48:49]
	v_pk_mul_f32 v[6:7], v[12:13], v[6:7]
	v_pk_mul_f32 v[8:9], v[10:11], v[8:9]
	v_cvt_pk_bf16_f32 v7, v6, v7
	v_cvt_pk_bf16_f32 v6, v8, v9
	v_mov_b64_e32 v[8:9], s[8:9]
	v_mad_i64_i32 v[8:9], s[38:39], v104, s83, v[8:9]
	v_lshl_add_u64 v[8:9], v[194:195], 1, v[8:9]
	global_store_dwordx2 v[8:9], v[6:7], off offset:8
; #define LAS __attribute__((address_space(3)))
; __device__ __forceinline__ float bf2f(unsigned v) { return __uint_as_float(v << 16); }
; __device__ __forceinline__ unsigned pk2(float lo, float hi) { f32x2 v; v.x = lo; v.y = hi; return __builtin_bit_cast(unsigned, __builtin_convertvector(v, hwbf2)); }
;     __device__ __forceinline__ void operator()(const f32x4 (&acc)[2][2][4][2], const pg8::Unit& u, int wr, int wc, int fr_, int fq_) const {
;     ...
; #pragma unroll
;             for (int i = 0; i < 4; ++i) {
;                 const int lr = 4 * rs + i, row = rowbase + lr;
;                 const u32x2 q0 = *(const LAS u32x2*)(slab + lr * SLAB_LD + cq * 8);
;                 f32x4 cur; cur[0] = bf2f(q0.x & 0xffff); cur[1] = bf2f(q0.x >> 16); cur[2] = bf2f(q0.y & 0xffff); cur[3] = bf2f(q0.y >> 16);
;                 const bool smp = row >= RP;
;                 const int t = smp ? ((row - RP) & (DSEQ - 1)) : (row & (SEQ - 1));
;                 const bool valid = (lr >= 2) && (row < R) && (t >= 2);
;                 const f32x4 cv = bb + w0 * p2 + w1 * p1 + w2 * cur;
;                 p2 = p1; p1 = cur;
;                 if (bj == 0) { cgv[i][0] = cv[0]; cgv[i][1] = cv[1]; cgv[i][2] = cv[2]; cgv[i][3] = cv[3]; }
;                 else { u32x2 w; w.x = pk2(gelu_tanh(cgv[i][0]) * cv[0], gelu_tanh(cgv[i][1]) * cv[1]); w.y = pk2(gelu_tanh(cgv[i][2]) * cv[2], gelu_tanh(cgv[i][3]) * cv[3]); if (valid) *(u32x2*)(act + (size_t)row * DFF + j0 + 4 * n) = w; }
;             }
.LBB0_1159:
	s_or_b64 exec, exec, s[42:43]
	ds_read_b64 v[8:9], v225 offset:40
	v_lshlrev_b32_e32 v10, 16, v16
	v_and_b32_e32 v11, 0xffff0000, v16
	v_lshlrev_b32_e32 v12, 16, v17
	v_and_b32_e32 v13, 0xffff0000, v17
	s_waitcnt lgkmcnt(0)
	v_lshlrev_b32_e32 v6, 16, v8
	v_and_b32_e32 v7, 0xffff0000, v8
	v_lshlrev_b32_e32 v8, 16, v9
	v_and_b32_e32 v9, 0xffff0000, v9
	s_and_saveexec_b64 s[38:39], s[2:3]
	s_cbranch_execz .LBB0_1161
	v_pk_fma_f32 v[16:17], v[74:75], v[26:27], v[78:79]
	v_pk_fma_f32 v[24:25], v[72:73], v[24:25], v[76:77]
	v_pk_fma_f32 v[16:17], v[70:71], v[4:5], v[16:17]
	v_pk_fma_f32 v[24:25], v[68:69], v[22:23], v[24:25]
	v_pk_fma_f32 v[16:17], v[66:67], v[12:13], v[16:17]
	v_pk_fma_f32 v[24:25], v[64:65], v[10:11], v[24:25]
	v_pk_fma_f32 v[26:27], v[42:43], v[28:29], v[46:47]
	v_mul_f32_e32 v28, v16, v16
	v_mul_f32_e32 v29, v17, v17
	v_mul_f32_e32 v30, v24, v24
	v_mul_f32_e32 v31, v25, v25
	v_fmamk_f32 v28, v28, 0xbdd2d3e2, v221
	v_fmamk_f32 v29, v29, 0xbdd2d3e2, v221
	v_fmamk_f32 v30, v30, 0xbdd2d3e2, v221
	v_fmamk_f32 v31, v31, 0xbdd2d3e2, v221
	v_mul_f32_e32 v28, v16, v28
	v_mul_f32_e32 v29, v17, v29
	v_mul_f32_e32 v30, v24, v30
	v_mul_f32_e32 v31, v25, v31
	v_exp_f32_e32 v28, v28
	v_exp_f32_e32 v29, v29
	v_exp_f32_e32 v30, v30
	v_exp_f32_e32 v31, v31
	v_add_f32_e32 v28, 1.0, v28
	v_add_f32_e32 v29, 1.0, v29
	v_add_f32_e32 v30, 1.0, v30
	v_add_f32_e32 v31, 1.0, v31
	v_rcp_f32_e32 v28, v28
	v_rcp_f32_e32 v29, v29
	v_rcp_f32_e32 v30, v30
	v_rcp_f32_e32 v31, v31
	v_pk_fma_f32 v[14:15], v[40:41], v[14:15], v[44:45]
	v_pk_fma_f32 v[26:27], v[38:39], v[2:3], v[26:27]
	v_pk_fma_f32 v[14:15], v[36:37], v[0:1], v[14:15]
	v_pk_fma_f32 v[26:27], v[34:35], v[8:9], v[26:27]
	v_pk_fma_f32 v[14:15], v[32:33], v[6:7], v[14:15]
	v_pk_mul_f32 v[16:17], v[16:17], v[28:29]
	v_pk_mul_f32 v[24:25], v[24:25], v[30:31]
	v_pk_mul_f32 v[16:17], v[16:17], v[26:27]
	v_pk_mul_f32 v[14:15], v[24:25], v[14:15]
	v_cvt_pk_bf16_f32 v17, v16, v17
	v_cvt_pk_bf16_f32 v16, v14, v15
	v_mov_b64_e32 v[14:15], s[8:9]
	v_mad_i64_i32 v[14:15], s[2:3], v62, s83, v[14:15]
	v_lshl_add_u64 v[14:15], v[194:195], 1, v[14:15]
	global_store_dwordx2 v[14:15], v[16:17], off offset:8
.LBB0_1161:
	s_or_b64 exec, exec, s[38:39]
	ds_read_b64 v[16:17], v225 offset:80
	v_lshlrev_b32_e32 v24, 16, v18
	v_and_b32_e32 v25, 0xffff0000, v18
	v_lshlrev_b32_e32 v18, 16, v19
	v_and_b32_e32 v19, 0xffff0000, v19
	s_waitcnt lgkmcnt(0)
	v_lshlrev_b32_e32 v14, 16, v16
	v_and_b32_e32 v15, 0xffff0000, v16
	v_lshlrev_b32_e32 v16, 16, v17
	v_and_b32_e32 v17, 0xffff0000, v17
	s_and_saveexec_b64 s[2:3], s[40:41]
	s_cbranch_execz .LBB0_1163
	v_pk_fma_f32 v[4:5], v[74:75], v[4:5], v[78:79]
	v_pk_fma_f32 v[22:23], v[72:73], v[22:23], v[76:77]
	v_pk_fma_f32 v[4:5], v[70:71], v[12:13], v[4:5]
	v_pk_fma_f32 v[22:23], v[68:69], v[10:11], v[22:23]
	v_pk_fma_f32 v[4:5], v[66:67], v[18:19], v[4:5]
	v_pk_fma_f32 v[22:23], v[64:65], v[24:25], v[22:23]
	v_mul_f32_e32 v26, v4, v4
	v_mul_f32_e32 v27, v5, v5
	v_fmamk_f32 v26, v26, 0xbdd2d3e2, v221
	v_fmamk_f32 v27, v27, 0xbdd2d3e2, v221
	v_mul_f32_e32 v28, v22, v22
	v_mul_f32_e32 v29, v23, v23
	v_mul_f32_e32 v26, v4, v26
	v_mul_f32_e32 v27, v5, v27
	v_fmamk_f32 v28, v28, 0xbdd2d3e2, v221
	v_fmamk_f32 v29, v29, 0xbdd2d3e2, v221
	v_exp_f32_e32 v26, v26
	v_exp_f32_e32 v27, v27
	v_mul_f32_e32 v28, v22, v28
	v_mul_f32_e32 v29, v23, v29
	v_exp_f32_e32 v28, v28
	v_exp_f32_e32 v29, v29
	v_add_f32_e32 v26, 1.0, v26
	v_add_f32_e32 v27, 1.0, v27
	v_rcp_f32_e32 v26, v26
	v_rcp_f32_e32 v27, v27
	v_add_f32_e32 v28, 1.0, v28
	v_add_f32_e32 v29, 1.0, v29
	v_rcp_f32_e32 v28, v28
	v_rcp_f32_e32 v29, v29
	v_pk_fma_f32 v[2:3], v[42:43], v[2:3], v[46:47]
	v_pk_fma_f32 v[0:1], v[40:41], v[0:1], v[44:45]
	v_pk_fma_f32 v[2:3], v[38:39], v[8:9], v[2:3]
	v_pk_fma_f32 v[0:1], v[36:37], v[6:7], v[0:1]
	v_pk_fma_f32 v[2:3], v[34:35], v[16:17], v[2:3]
	v_pk_mul_f32 v[4:5], v[4:5], v[26:27]
	v_pk_fma_f32 v[0:1], v[32:33], v[14:15], v[0:1]
	v_pk_mul_f32 v[2:3], v[4:5], v[2:3]
	v_pk_mul_f32 v[4:5], v[22:23], v[28:29]
	v_cvt_pk_bf16_f32 v3, v2, v3
	v_pk_mul_f32 v[0:1], v[4:5], v[0:1]
	s_nop 0
	v_cvt_pk_bf16_f32 v2, v0, v1
	v_mov_b64_e32 v[0:1], s[8:9]
	v_mad_i64_i32 v[0:1], s[38:39], v58, s83, v[0:1]
	v_lshl_add_u64 v[0:1], v[194:195], 1, v[0:1]
	global_store_dwordx2 v[0:1], v[2:3], off offset:8
.LBB0_1163:
	s_or_b64 exec, exec, s[2:3]
	s_and_saveexec_b64 s[2:3], s[4:5]
	s_cbranch_execz .LBB0_1122
	v_pk_fma_f32 v[2:3], v[72:73], v[10:11], v[76:77]
	v_lshlrev_b32_e32 v4, 16, v20
	v_pk_fma_f32 v[2:3], v[68:69], v[24:25], v[2:3]
	v_and_b32_e32 v5, 0xffff0000, v20
	v_pk_fma_f32 v[2:3], v[64:65], v[4:5], v[2:3]
	ds_read_b64 v[4:5], v224
	v_pk_fma_f32 v[0:1], v[74:75], v[12:13], v[78:79]
	v_lshlrev_b32_e32 v10, 16, v21
	v_pk_fma_f32 v[0:1], v[70:71], v[18:19], v[0:1]
	v_and_b32_e32 v11, 0xffff0000, v21
	v_pk_fma_f32 v[6:7], v[40:41], v[6:7], v[44:45]
	v_pk_fma_f32 v[0:1], v[66:67], v[10:11], v[0:1]
	v_pk_fma_f32 v[6:7], v[36:37], v[14:15], v[6:7]
	s_waitcnt lgkmcnt(0)
	v_lshlrev_b32_e32 v10, 16, v4
	v_and_b32_e32 v11, 0xffff0000, v4
	v_pk_fma_f32 v[6:7], v[32:33], v[10:11], v[6:7]
	v_mul_f32_e32 v10, v0, v0
	v_mul_f32_e32 v11, v1, v1
	v_fmamk_f32 v10, v10, 0xbdd2d3e2, v221
	v_fmamk_f32 v11, v11, 0xbdd2d3e2, v221
	v_mul_f32_e32 v10, v0, v10
	v_mul_f32_e32 v11, v1, v11
	v_exp_f32_e32 v10, v10
	v_exp_f32_e32 v11, v11
	v_pk_fma_f32 v[8:9], v[42:43], v[8:9], v[46:47]
	v_lshlrev_b32_e32 v4, 16, v5
	v_pk_fma_f32 v[8:9], v[38:39], v[16:17], v[8:9]
	v_and_b32_e32 v5, 0xffff0000, v5
	v_pk_fma_f32 v[4:5], v[34:35], v[4:5], v[8:9]
	v_add_f32_e32 v8, 1.0, v10
	v_add_f32_e32 v9, 1.0, v11
	v_mul_f32_e32 v10, v2, v2
	v_mul_f32_e32 v11, v3, v3
	v_fmamk_f32 v10, v10, 0xbdd2d3e2, v221
	v_fmamk_f32 v11, v11, 0xbdd2d3e2, v221
	v_mul_f32_e32 v10, v2, v10
	v_mul_f32_e32 v11, v3, v11
	v_exp_f32_e32 v10, v10
	v_exp_f32_e32 v11, v11
	v_rcp_f32_e32 v8, v8
	v_rcp_f32_e32 v9, v9
	v_add_f32_e32 v10, 1.0, v10
	v_add_f32_e32 v11, 1.0, v11
	v_rcp_f32_e32 v10, v10
	v_rcp_f32_e32 v11, v11
	v_pk_mul_f32 v[0:1], v[0:1], v[8:9]
	v_pk_mul_f32 v[2:3], v[2:3], v[10:11]
	v_pk_mul_f32 v[0:1], v[0:1], v[4:5]
	v_pk_mul_f32 v[2:3], v[2:3], v[6:7]
	v_cvt_pk_bf16_f32 v1, v0, v1
	v_cvt_pk_bf16_f32 v0, v2, v3
	v_mov_b64_e32 v[2:3], s[8:9]
	v_mad_i64_i32 v[2:3], s[4:5], v54, s83, v[2:3]
	v_lshl_add_u64 v[2:3], v[194:195], 1, v[2:3]
	global_store_dwordx2 v[2:3], v[0:1], off offset:8
	s_branch .LBB0_1122
